# barrier: XCD leaders poll the cross-XCD arrival counter (>= target) instead of the generation word
# speedup vs baseline: 1.0045x; 1.0045x over previous
; DI unsigned xb_ld(unsigned* p) { return __hip_atomic_load(p, __ATOMIC_RELAXED, __HIP_MEMORY_SCOPE_AGENT); }
; DI unsigned xb_add(unsigned* p, unsigned v) { return __hip_atomic_fetch_add(p, v, __ATOMIC_RELAXED, __HIP_MEMORY_SCOPE_AGENT); }
; #define XB_SPIN(cond, bar) do { unsigned _sp = 0; while (cond) { __builtin_amdgcn_s_sleep(1); \
;     if ((++_sp & 255u) == 0u) { if (xb_ld(&(bar)[XB_TMO])) break; if (_sp > XB_SPIN_CAP) { atomicAdd(&(bar)[XB_TMO], 1u); break; } } } } while (0)
; DI void xcd_barrier(const XcdBarrier& b) {
;     ...
;       const unsigned og = xb_add(&bar[XB_TOP], 1u);
;       const unsigned tg = og / nx;
;       if (og + 1u == (tg + 1u) * nx) xb_add(&bar[XB_TOPGEN], 1u);
;       else XB_SPIN(xb_ld(&bar[XB_TOPGEN]) == tg, bar);
.LBB0_201:
	s_or_b64 exec, exec, s[14:15]
	v_cvt_f32_u32_e32 v3, v0
	s_waitcnt vmcnt(0)
	v_readfirstlane_b32 s0, v2
	s_add_u32 s14, s86, 0xe7c4500
	s_addc_u32 s15, s87, 0
	v_rcp_iflag_f32_e32 v3, v3
	v_add_u32_e32 v1, s0, v1
	v_add_u32_e32 v4, 1, v1
	s_mov_b64 s[16:17], -1
	v_mul_f32_e32 v2, 0x4f7ffffe, v3
	v_cvt_u32_f32_e32 v2, v2
	v_sub_u32_e32 v3, 0, v0
	v_mul_lo_u32 v3, v3, v2
	v_mul_hi_u32 v3, v2, v3
	v_add_u32_e32 v2, v2, v3
	v_mul_hi_u32 v2, v1, v2
	v_mul_lo_u32 v3, v2, v0
	v_sub_u32_e32 v1, v1, v3
	v_add_u32_e32 v5, 1, v2
	v_cmp_ge_u32_e32 vcc, v1, v0
	v_sub_u32_e32 v3, v1, v0
	s_nop 0
	v_cndmask_b32_e32 v2, v2, v5, vcc
	v_cndmask_b32_e32 v1, v1, v3, vcc
	v_add_u32_e32 v3, 1, v2
	v_cmp_ge_u32_e32 vcc, v1, v0
	s_nop 1
	v_cndmask_b32_e32 v2, v2, v3, vcc
	v_mul_lo_u32 v1, v0, v2
	v_add_u32_e32 v0, v1, v0
	v_cmp_ne_u32_e32 vcc, v4, v0
	v_mov_b32_e32 v232, v0
	v_mov_b64_e32 v[0:1], s[14:15]
	s_and_saveexec_b64 s[12:13], vcc
	s_cbranch_execz .LBB0_213
	v_mov_b32_e32 v0, 0
	v_mov_b32_e32 v233, 0xe7c4000
	global_load_dword v1, v233, s[86:87] offset:1024 sc1
	s_mov_b64 s[30:31], 0
	s_waitcnt vmcnt(0)
	v_cmp_lt_u32_e32 vcc, v1, v232
	s_and_saveexec_b64 s[20:21], vcc
	s_cbranch_execz .LBB0_212
	s_add_u32 s16, s86, 0xe7c1200
	s_addc_u32 s17, s87, 0
	s_mov_b32 s0, 1
	s_branch .LBB0_205

; DI unsigned xb_ld(unsigned* p) { return __hip_atomic_load(p, __ATOMIC_RELAXED, __HIP_MEMORY_SCOPE_AGENT); }
; #define XB_SPIN(cond, bar) do { unsigned _sp = 0; while (cond) { __builtin_amdgcn_s_sleep(1); \
;     if ((++_sp & 255u) == 0u) { if (xb_ld(&(bar)[XB_TMO])) break; if (_sp > XB_SPIN_CAP) { atomicAdd(&(bar)[XB_TMO], 1u); break; } } } } while (0)
; DI void xcd_barrier(const XcdBarrier& b) {
;     ...
;       else XB_SPIN(xb_ld(&bar[XB_TOPGEN]) == tg, bar);
.LBB0_209:
	global_load_dword v1, v233, s[86:87] offset:1024 sc1
	s_add_i32 s0, s0, 1
	s_mov_b64 s[36:37], -1
	s_waitcnt vmcnt(0)
	v_cmp_ge_u32_e32 vcc, v1, v232
	s_orn2_b64 s[44:45], vcc, exec
	s_branch .LBB0_204

; DI unsigned xb_ld(unsigned* p) { return __hip_atomic_load(p, __ATOMIC_RELAXED, __HIP_MEMORY_SCOPE_AGENT); }
; DI unsigned xb_add(unsigned* p, unsigned v) { return __hip_atomic_fetch_add(p, v, __ATOMIC_RELAXED, __HIP_MEMORY_SCOPE_AGENT); }
; #define XB_SPIN(cond, bar) do { unsigned _sp = 0; while (cond) { __builtin_amdgcn_s_sleep(1); \
;     if ((++_sp & 255u) == 0u) { if (xb_ld(&(bar)[XB_TMO])) break; if (_sp > XB_SPIN_CAP) { atomicAdd(&(bar)[XB_TMO], 1u); break; } } } } while (0)
; DI void xcd_barrier(const XcdBarrier& b) {
;     ...
;       const unsigned og = xb_add(&bar[XB_TOP], 1u);
;       const unsigned tg = og / nx;
;       if (og + 1u == (tg + 1u) * nx) xb_add(&bar[XB_TOPGEN], 1u);
;       else XB_SPIN(xb_ld(&bar[XB_TOPGEN]) == tg, bar);
.LBB0_266:
	s_or_b64 exec, exec, s[12:13]
	v_cvt_f32_u32_e32 v3, v0
	s_waitcnt vmcnt(0)
	v_readfirstlane_b32 s0, v2
	s_add_u32 s12, s86, 0xe7c4500
	s_addc_u32 s13, s87, 0
	v_rcp_iflag_f32_e32 v3, v3
	v_add_u32_e32 v1, s0, v1
	v_add_u32_e32 v4, 1, v1
	s_mov_b64 s[14:15], -1
	v_mul_f32_e32 v2, 0x4f7ffffe, v3
	v_cvt_u32_f32_e32 v2, v2
	v_sub_u32_e32 v3, 0, v0
	v_mul_lo_u32 v3, v3, v2
	v_mul_hi_u32 v3, v2, v3
	v_add_u32_e32 v2, v2, v3
	v_mul_hi_u32 v2, v1, v2
	v_mul_lo_u32 v3, v2, v0
	v_sub_u32_e32 v1, v1, v3
	v_add_u32_e32 v5, 1, v2
	v_cmp_ge_u32_e32 vcc, v1, v0
	v_sub_u32_e32 v3, v1, v0
	s_nop 0
	v_cndmask_b32_e32 v2, v2, v5, vcc
	v_cndmask_b32_e32 v1, v1, v3, vcc
	v_add_u32_e32 v3, 1, v2
	v_cmp_ge_u32_e32 vcc, v1, v0
	s_nop 1
	v_cndmask_b32_e32 v2, v2, v3, vcc
	v_mul_lo_u32 v1, v0, v2
	v_add_u32_e32 v0, v1, v0
	v_cmp_ne_u32_e32 vcc, v4, v0
	v_mov_b32_e32 v232, v0
	v_mov_b64_e32 v[0:1], s[12:13]
	s_and_saveexec_b64 s[10:11], vcc
	s_cbranch_execz .LBB0_278
	v_mov_b32_e32 v0, 0
	v_mov_b32_e32 v233, 0xe7c4000
	global_load_dword v1, v233, s[86:87] offset:1024 sc1
	s_mov_b64 s[20:21], 0
	s_waitcnt vmcnt(0)
	v_cmp_lt_u32_e32 vcc, v1, v232
	s_and_saveexec_b64 s[16:17], vcc
	s_cbranch_execz .LBB0_277
	s_add_u32 s14, s86, 0xe7c1200
	s_addc_u32 s15, s87, 0
	s_mov_b32 s0, 1
	s_branch .LBB0_270

; DI unsigned xb_ld(unsigned* p) { return __hip_atomic_load(p, __ATOMIC_RELAXED, __HIP_MEMORY_SCOPE_AGENT); }
; DI unsigned xb_add(unsigned* p, unsigned v) { return __hip_atomic_fetch_add(p, v, __ATOMIC_RELAXED, __HIP_MEMORY_SCOPE_AGENT); }
; #define XB_SPIN(cond, bar) do { unsigned _sp = 0; while (cond) { __builtin_amdgcn_s_sleep(1); \
;     if ((++_sp & 255u) == 0u) { if (xb_ld(&(bar)[XB_TMO])) break; if (_sp > XB_SPIN_CAP) { atomicAdd(&(bar)[XB_TMO], 1u); break; } } } } while (0)
; DI void xcd_barrier(const XcdBarrier& b) {
;     ...
;       const unsigned og = xb_add(&bar[XB_TOP], 1u);
;       const unsigned tg = og / nx;
;       if (og + 1u == (tg + 1u) * nx) xb_add(&bar[XB_TOPGEN], 1u);
;       else XB_SPIN(xb_ld(&bar[XB_TOPGEN]) == tg, bar);
.LBB0_507:
	s_or_b64 exec, exec, s[12:13]
	v_cvt_f32_u32_e32 v3, v0
	s_waitcnt vmcnt(0)
	v_readfirstlane_b32 s0, v2
	s_add_u32 s12, s86, 0xe7c4500
	s_addc_u32 s13, s87, 0
	v_rcp_iflag_f32_e32 v3, v3
	v_add_u32_e32 v1, s0, v1
	v_add_u32_e32 v4, 1, v1
	s_mov_b64 s[14:15], -1
	v_mul_f32_e32 v2, 0x4f7ffffe, v3
	v_cvt_u32_f32_e32 v2, v2
	v_sub_u32_e32 v3, 0, v0
	v_mul_lo_u32 v3, v3, v2
	v_mul_hi_u32 v3, v2, v3
	v_add_u32_e32 v2, v2, v3
	v_mul_hi_u32 v2, v1, v2
	v_mul_lo_u32 v3, v2, v0
	v_sub_u32_e32 v1, v1, v3
	v_add_u32_e32 v5, 1, v2
	v_cmp_ge_u32_e32 vcc, v1, v0
	v_sub_u32_e32 v3, v1, v0
	s_nop 0
	v_cndmask_b32_e32 v2, v2, v5, vcc
	v_cndmask_b32_e32 v1, v1, v3, vcc
	v_add_u32_e32 v3, 1, v2
	v_cmp_ge_u32_e32 vcc, v1, v0
	s_nop 1
	v_cndmask_b32_e32 v2, v2, v3, vcc
	v_mul_lo_u32 v1, v0, v2
	v_add_u32_e32 v0, v1, v0
	v_cmp_ne_u32_e32 vcc, v4, v0
	v_mov_b32_e32 v232, v0
	v_mov_b64_e32 v[0:1], s[12:13]
	s_and_saveexec_b64 s[10:11], vcc
	s_cbranch_execz .LBB0_519
	v_mov_b32_e32 v0, 0
	v_mov_b32_e32 v233, 0xe7c4000
	global_load_dword v1, v233, s[86:87] offset:1024 sc1
	s_mov_b64 s[30:31], 0
	s_waitcnt vmcnt(0)
	v_cmp_lt_u32_e32 vcc, v1, v232
	s_and_saveexec_b64 s[16:17], vcc
	s_cbranch_execz .LBB0_518
	s_add_u32 s14, s86, 0xe7c1200
	s_addc_u32 s15, s87, 0
	s_mov_b32 s0, 1
	s_branch .LBB0_511

; DI unsigned xb_ld(unsigned* p) { return __hip_atomic_load(p, __ATOMIC_RELAXED, __HIP_MEMORY_SCOPE_AGENT); }
; DI unsigned xb_add(unsigned* p, unsigned v) { return __hip_atomic_fetch_add(p, v, __ATOMIC_RELAXED, __HIP_MEMORY_SCOPE_AGENT); }
; #define XB_SPIN(cond, bar) do { unsigned _sp = 0; while (cond) { __builtin_amdgcn_s_sleep(1); \
;     if ((++_sp & 255u) == 0u) { if (xb_ld(&(bar)[XB_TMO])) break; if (_sp > XB_SPIN_CAP) { atomicAdd(&(bar)[XB_TMO], 1u); break; } } } } while (0)
; DI void xcd_barrier(const XcdBarrier& b) {
;     ...
;       const unsigned og = xb_add(&bar[XB_TOP], 1u);
;       const unsigned tg = og / nx;
;       if (og + 1u == (tg + 1u) * nx) xb_add(&bar[XB_TOPGEN], 1u);
;       else XB_SPIN(xb_ld(&bar[XB_TOPGEN]) == tg, bar);
.LBB0_846:
	s_or_b64 exec, exec, s[12:13]
	v_cvt_f32_u32_e32 v3, v0
	s_waitcnt vmcnt(0)
	v_readfirstlane_b32 s0, v2
	s_add_u32 s12, s86, 0xe7c4500
	s_addc_u32 s13, s87, 0
	v_rcp_iflag_f32_e32 v3, v3
	v_add_u32_e32 v1, s0, v1
	v_add_u32_e32 v4, 1, v1
	s_mov_b64 s[14:15], -1
	v_mul_f32_e32 v2, 0x4f7ffffe, v3
	v_cvt_u32_f32_e32 v2, v2
	v_sub_u32_e32 v3, 0, v0
	v_mul_lo_u32 v3, v3, v2
	v_mul_hi_u32 v3, v2, v3
	v_add_u32_e32 v2, v2, v3
	v_mul_hi_u32 v2, v1, v2
	v_mul_lo_u32 v3, v2, v0
	v_sub_u32_e32 v1, v1, v3
	v_add_u32_e32 v5, 1, v2
	v_cmp_ge_u32_e32 vcc, v1, v0
	v_sub_u32_e32 v3, v1, v0
	s_nop 0
	v_cndmask_b32_e32 v2, v2, v5, vcc
	v_cndmask_b32_e32 v1, v1, v3, vcc
	v_add_u32_e32 v3, 1, v2
	v_cmp_ge_u32_e32 vcc, v1, v0
	s_nop 1
	v_cndmask_b32_e32 v2, v2, v3, vcc
	v_mul_lo_u32 v1, v0, v2
	v_add_u32_e32 v0, v1, v0
	v_cmp_ne_u32_e32 vcc, v4, v0
	v_mov_b32_e32 v232, v0
	v_mov_b64_e32 v[0:1], s[12:13]
	s_and_saveexec_b64 s[10:11], vcc
	s_cbranch_execz .LBB0_858
	v_mov_b32_e32 v0, 0
	v_mov_b32_e32 v233, 0xe7c4000
	global_load_dword v1, v233, s[86:87] offset:1024 sc1
	s_mov_b64 s[26:27], 0
	s_waitcnt vmcnt(0)
	v_cmp_lt_u32_e32 vcc, v1, v232
	s_and_saveexec_b64 s[16:17], vcc
	s_cbranch_execz .LBB0_857
	s_add_u32 s14, s86, 0xe7c1200
	s_addc_u32 s15, s87, 0
	s_mov_b32 s0, 1
	s_branch .LBB0_850

; DI unsigned xb_ld(unsigned* p) { return __hip_atomic_load(p, __ATOMIC_RELAXED, __HIP_MEMORY_SCOPE_AGENT); }
; #define XB_SPIN(cond, bar) do { unsigned _sp = 0; while (cond) { __builtin_amdgcn_s_sleep(1); \
;     if ((++_sp & 255u) == 0u) { if (xb_ld(&(bar)[XB_TMO])) break; if (_sp > XB_SPIN_CAP) { atomicAdd(&(bar)[XB_TMO], 1u); break; } } } } while (0)
; DI void xcd_barrier(const XcdBarrier& b) {
;     ...
;       else XB_SPIN(xb_ld(&bar[XB_TOPGEN]) == tg, bar);
.LBB0_854:
	global_load_dword v1, v233, s[86:87] offset:1024 sc1
	s_add_i32 s0, s0, 1
	s_mov_b64 s[30:31], -1
	s_waitcnt vmcnt(0)
	v_cmp_ge_u32_e32 vcc, v1, v232
	s_orn2_b64 s[36:37], vcc, exec
	s_branch .LBB0_849

; DI unsigned xb_ld(unsigned* p) { return __hip_atomic_load(p, __ATOMIC_RELAXED, __HIP_MEMORY_SCOPE_AGENT); }
; DI unsigned xb_add(unsigned* p, unsigned v) { return __hip_atomic_fetch_add(p, v, __ATOMIC_RELAXED, __HIP_MEMORY_SCOPE_AGENT); }
; #define XB_SPIN(cond, bar) do { unsigned _sp = 0; while (cond) { __builtin_amdgcn_s_sleep(1); \
;     if ((++_sp & 255u) == 0u) { if (xb_ld(&(bar)[XB_TMO])) break; if (_sp > XB_SPIN_CAP) { atomicAdd(&(bar)[XB_TMO], 1u); break; } } } } while (0)
; DI void xcd_barrier(const XcdBarrier& b) {
;     ...
;       const unsigned og = xb_add(&bar[XB_TOP], 1u);
;       const unsigned tg = og / nx;
;       if (og + 1u == (tg + 1u) * nx) xb_add(&bar[XB_TOPGEN], 1u);
;       else XB_SPIN(xb_ld(&bar[XB_TOPGEN]) == tg, bar);
.LBB0_958:
	s_or_b64 exec, exec, s[12:13]
	v_cvt_f32_u32_e32 v3, v0
	s_waitcnt vmcnt(0)
	v_readfirstlane_b32 s0, v2
	s_add_u32 s12, s86, 0xe7c4500
	s_addc_u32 s13, s87, 0
	v_rcp_iflag_f32_e32 v3, v3
	v_add_u32_e32 v1, s0, v1
	v_add_u32_e32 v4, 1, v1
	s_mov_b64 s[14:15], -1
	v_mul_f32_e32 v2, 0x4f7ffffe, v3
	v_cvt_u32_f32_e32 v2, v2
	v_sub_u32_e32 v3, 0, v0
	v_mul_lo_u32 v3, v3, v2
	v_mul_hi_u32 v3, v2, v3
	v_add_u32_e32 v2, v2, v3
	v_mul_hi_u32 v2, v1, v2
	v_mul_lo_u32 v3, v2, v0
	v_sub_u32_e32 v1, v1, v3
	v_add_u32_e32 v5, 1, v2
	v_cmp_ge_u32_e32 vcc, v1, v0
	v_sub_u32_e32 v3, v1, v0
	s_nop 0
	v_cndmask_b32_e32 v2, v2, v5, vcc
	v_cndmask_b32_e32 v1, v1, v3, vcc
	v_add_u32_e32 v3, 1, v2
	v_cmp_ge_u32_e32 vcc, v1, v0
	s_nop 1
	v_cndmask_b32_e32 v2, v2, v3, vcc
	v_mul_lo_u32 v1, v0, v2
	v_add_u32_e32 v0, v1, v0
	v_cmp_ne_u32_e32 vcc, v4, v0
	v_mov_b32_e32 v232, v0
	v_mov_b64_e32 v[0:1], s[12:13]
	s_and_saveexec_b64 s[10:11], vcc
	s_cbranch_execz .LBB0_970
	v_mov_b32_e32 v0, 0
	v_mov_b32_e32 v233, 0xe7c4000
	global_load_dword v1, v233, s[86:87] offset:1024 sc1
	s_mov_b64 s[24:25], 0
	s_waitcnt vmcnt(0)
	v_cmp_lt_u32_e32 vcc, v1, v232
	s_and_saveexec_b64 s[16:17], vcc
	s_cbranch_execz .LBB0_969
	s_add_u32 s14, s86, 0xe7c1200
	s_addc_u32 s15, s87, 0
	s_mov_b32 s0, 1
	s_branch .LBB0_962

; DI unsigned xb_ld(unsigned* p) { return __hip_atomic_load(p, __ATOMIC_RELAXED, __HIP_MEMORY_SCOPE_AGENT); }
; #define XB_SPIN(cond, bar) do { unsigned _sp = 0; while (cond) { __builtin_amdgcn_s_sleep(1); \
;     if ((++_sp & 255u) == 0u) { if (xb_ld(&(bar)[XB_TMO])) break; if (_sp > XB_SPIN_CAP) { atomicAdd(&(bar)[XB_TMO], 1u); break; } } } } while (0)
; DI void xcd_barrier(const XcdBarrier& b) {
;     ...
;       else XB_SPIN(xb_ld(&bar[XB_TOPGEN]) == tg, bar);
.LBB0_966:
	global_load_dword v1, v233, s[86:87] offset:1024 sc1
	s_add_i32 s0, s0, 1
	s_mov_b64 s[28:29], -1
	s_waitcnt vmcnt(0)
	v_cmp_ge_u32_e32 vcc, v1, v232
	s_orn2_b64 s[34:35], vcc, exec
	s_branch .LBB0_961

; DI unsigned xb_ld(unsigned* p) { return __hip_atomic_load(p, __ATOMIC_RELAXED, __HIP_MEMORY_SCOPE_AGENT); }
; DI unsigned xb_add(unsigned* p, unsigned v) { return __hip_atomic_fetch_add(p, v, __ATOMIC_RELAXED, __HIP_MEMORY_SCOPE_AGENT); }
; #define XB_SPIN(cond, bar) do { unsigned _sp = 0; while (cond) { __builtin_amdgcn_s_sleep(1); \
;     if ((++_sp & 255u) == 0u) { if (xb_ld(&(bar)[XB_TMO])) break; if (_sp > XB_SPIN_CAP) { atomicAdd(&(bar)[XB_TMO], 1u); break; } } } } while (0)
; DI void xcd_barrier(const XcdBarrier& b) {
;     ...
;       const unsigned og = xb_add(&bar[XB_TOP], 1u);
;       const unsigned tg = og / nx;
;       if (og + 1u == (tg + 1u) * nx) xb_add(&bar[XB_TOPGEN], 1u);
;       else XB_SPIN(xb_ld(&bar[XB_TOPGEN]) == tg, bar);
.LBB0_1084:
	s_or_b64 exec, exec, s[22:23]
	v_cvt_f32_u32_e32 v3, v0
	s_waitcnt vmcnt(0)
	v_readfirstlane_b32 s0, v2
	s_add_u32 s22, s86, 0xe7c4500
	s_addc_u32 s23, s87, 0
	v_rcp_iflag_f32_e32 v3, v3
	v_add_u32_e32 v1, s0, v1
	v_add_u32_e32 v4, 1, v1
	s_mov_b64 s[24:25], -1
	v_mul_f32_e32 v2, 0x4f7ffffe, v3
	v_cvt_u32_f32_e32 v2, v2
	v_sub_u32_e32 v3, 0, v0
	v_mul_lo_u32 v3, v3, v2
	v_mul_hi_u32 v3, v2, v3
	v_add_u32_e32 v2, v2, v3
	v_mul_hi_u32 v2, v1, v2
	v_mul_lo_u32 v3, v2, v0
	v_sub_u32_e32 v1, v1, v3
	v_add_u32_e32 v5, 1, v2
	v_cmp_ge_u32_e32 vcc, v1, v0
	v_sub_u32_e32 v3, v1, v0
	s_nop 0
	v_cndmask_b32_e32 v2, v2, v5, vcc
	v_cndmask_b32_e32 v1, v1, v3, vcc
	v_add_u32_e32 v3, 1, v2
	v_cmp_ge_u32_e32 vcc, v1, v0
	s_nop 1
	v_cndmask_b32_e32 v2, v2, v3, vcc
	v_mul_lo_u32 v1, v0, v2
	v_add_u32_e32 v0, v1, v0
	v_cmp_ne_u32_e32 vcc, v4, v0
	v_mov_b32_e32 v232, v0
	v_mov_b64_e32 v[0:1], s[22:23]
	s_and_saveexec_b64 s[16:17], vcc
	s_cbranch_execz .LBB0_1096
	v_mov_b32_e32 v0, 0
	v_mov_b32_e32 v233, 0xe7c4000
	global_load_dword v1, v233, s[86:87] offset:1024 sc1
	s_mov_b64 s[28:29], 0
	s_waitcnt vmcnt(0)
	v_cmp_lt_u32_e32 vcc, v1, v232
	s_and_saveexec_b64 s[26:27], vcc
	s_cbranch_execz .LBB0_1095
	s_add_u32 s24, s86, 0xe7c1200
	s_addc_u32 s25, s87, 0
	s_mov_b32 s0, 1
	s_branch .LBB0_1088

; DI unsigned xb_ld(unsigned* p) { return __hip_atomic_load(p, __ATOMIC_RELAXED, __HIP_MEMORY_SCOPE_AGENT); }
; #define XB_SPIN(cond, bar) do { unsigned _sp = 0; while (cond) { __builtin_amdgcn_s_sleep(1); \
;     if ((++_sp & 255u) == 0u) { if (xb_ld(&(bar)[XB_TMO])) break; if (_sp > XB_SPIN_CAP) { atomicAdd(&(bar)[XB_TMO], 1u); break; } } } } while (0)
; DI void xcd_barrier(const XcdBarrier& b) {
;     ...
;       else XB_SPIN(xb_ld(&bar[XB_TOPGEN]) == tg, bar);
.LBB0_1092:
	global_load_dword v1, v233, s[86:87] offset:1024 sc1
	s_add_i32 s0, s0, 1
	s_mov_b64 s[34:35], -1
	s_waitcnt vmcnt(0)
	v_cmp_ge_u32_e32 vcc, v1, v232
	s_orn2_b64 s[42:43], vcc, exec
	s_branch .LBB0_1087

; DI unsigned xb_ld(unsigned* p) { return __hip_atomic_load(p, __ATOMIC_RELAXED, __HIP_MEMORY_SCOPE_AGENT); }
; DI unsigned xb_add(unsigned* p, unsigned v) { return __hip_atomic_fetch_add(p, v, __ATOMIC_RELAXED, __HIP_MEMORY_SCOPE_AGENT); }
; #define XB_SPIN(cond, bar) do { unsigned _sp = 0; while (cond) { __builtin_amdgcn_s_sleep(1); \
;     if ((++_sp & 255u) == 0u) { if (xb_ld(&(bar)[XB_TMO])) break; if (_sp > XB_SPIN_CAP) { atomicAdd(&(bar)[XB_TMO], 1u); break; } } } } while (0)
; DI void xcd_barrier(const XcdBarrier& b) {
;     ...
;       const unsigned og = xb_add(&bar[XB_TOP], 1u);
;       const unsigned tg = og / nx;
;       if (og + 1u == (tg + 1u) * nx) xb_add(&bar[XB_TOPGEN], 1u);
;       else XB_SPIN(xb_ld(&bar[XB_TOPGEN]) == tg, bar);
.LBB0_1153:
	s_or_b64 exec, exec, s[12:13]
	v_cvt_f32_u32_e32 v3, v0
	s_waitcnt vmcnt(0)
	v_readfirstlane_b32 s0, v2
	s_add_u32 s12, s86, 0xe7c4500
	s_addc_u32 s13, s87, 0
	v_rcp_iflag_f32_e32 v3, v3
	v_add_u32_e32 v1, s0, v1
	v_add_u32_e32 v4, 1, v1
	s_mov_b64 s[14:15], -1
	v_mul_f32_e32 v2, 0x4f7ffffe, v3
	v_cvt_u32_f32_e32 v2, v2
	v_sub_u32_e32 v3, 0, v0
	v_mul_lo_u32 v3, v3, v2
	v_mul_hi_u32 v3, v2, v3
	v_add_u32_e32 v2, v2, v3
	v_mul_hi_u32 v2, v1, v2
	v_mul_lo_u32 v3, v2, v0
	v_sub_u32_e32 v1, v1, v3
	v_add_u32_e32 v5, 1, v2
	v_cmp_ge_u32_e32 vcc, v1, v0
	v_sub_u32_e32 v3, v1, v0
	s_nop 0
	v_cndmask_b32_e32 v2, v2, v5, vcc
	v_cndmask_b32_e32 v1, v1, v3, vcc
	v_add_u32_e32 v3, 1, v2
	v_cmp_ge_u32_e32 vcc, v1, v0
	s_nop 1
	v_cndmask_b32_e32 v2, v2, v3, vcc
	v_mul_lo_u32 v1, v0, v2
	v_add_u32_e32 v0, v1, v0
	v_cmp_ne_u32_e32 vcc, v4, v0
	v_mov_b32_e32 v232, v0
	v_mov_b64_e32 v[0:1], s[12:13]
	s_and_saveexec_b64 s[10:11], vcc
	s_cbranch_execz .LBB0_1165
	v_mov_b32_e32 v0, 0
	v_mov_b32_e32 v233, 0xe7c4000
	global_load_dword v1, v233, s[86:87] offset:1024 sc1
	s_mov_b64 s[22:23], 0
	s_waitcnt vmcnt(0)
	v_cmp_lt_u32_e32 vcc, v1, v232
	s_and_saveexec_b64 s[16:17], vcc
	s_cbranch_execz .LBB0_1164
	s_add_u32 s14, s86, 0xe7c1200
	s_addc_u32 s15, s87, 0
	s_mov_b32 s0, 1
	s_branch .LBB0_1157

; DI unsigned xb_ld(unsigned* p) { return __hip_atomic_load(p, __ATOMIC_RELAXED, __HIP_MEMORY_SCOPE_AGENT); }
; #define XB_SPIN(cond, bar) do { unsigned _sp = 0; while (cond) { __builtin_amdgcn_s_sleep(1); \
;     if ((++_sp & 255u) == 0u) { if (xb_ld(&(bar)[XB_TMO])) break; if (_sp > XB_SPIN_CAP) { atomicAdd(&(bar)[XB_TMO], 1u); break; } } } } while (0)
; DI void xcd_barrier(const XcdBarrier& b) {
;     ...
;       else XB_SPIN(xb_ld(&bar[XB_TOPGEN]) == tg, bar);
.LBB0_1161:
	global_load_dword v1, v233, s[86:87] offset:1024 sc1
	s_add_i32 s0, s0, 1
	s_mov_b64 s[26:27], -1
	s_waitcnt vmcnt(0)
	v_cmp_ge_u32_e32 vcc, v1, v232
	s_orn2_b64 s[30:31], vcc, exec
	s_branch .LBB0_1156

; DI unsigned xb_ld(unsigned* p) { return __hip_atomic_load(p, __ATOMIC_RELAXED, __HIP_MEMORY_SCOPE_AGENT); }
; DI unsigned xb_add(unsigned* p, unsigned v) { return __hip_atomic_fetch_add(p, v, __ATOMIC_RELAXED, __HIP_MEMORY_SCOPE_AGENT); }
; #define XB_SPIN(cond, bar) do { unsigned _sp = 0; while (cond) { __builtin_amdgcn_s_sleep(1); \
;     if ((++_sp & 255u) == 0u) { if (xb_ld(&(bar)[XB_TMO])) break; if (_sp > XB_SPIN_CAP) { atomicAdd(&(bar)[XB_TMO], 1u); break; } } } } while (0)
; DI void xcd_barrier(const XcdBarrier& b) {
;     ...
;       const unsigned og = xb_add(&bar[XB_TOP], 1u);
;       const unsigned tg = og / nx;
;       if (og + 1u == (tg + 1u) * nx) xb_add(&bar[XB_TOPGEN], 1u);
;       else XB_SPIN(xb_ld(&bar[XB_TOPGEN]) == tg, bar);
.LBB0_1210:
	s_or_b64 exec, exec, s[10:11]
	v_cvt_f32_u32_e32 v3, v0
	s_waitcnt vmcnt(0)
	v_readfirstlane_b32 s0, v2
	s_add_u32 s10, s86, 0xe7c4500
	s_addc_u32 s11, s87, 0
	v_rcp_iflag_f32_e32 v3, v3
	v_add_u32_e32 v1, s0, v1
	v_add_u32_e32 v4, 1, v1
	s_mov_b64 s[12:13], -1
	v_mul_f32_e32 v2, 0x4f7ffffe, v3
	v_cvt_u32_f32_e32 v2, v2
	v_sub_u32_e32 v3, 0, v0
	v_mul_lo_u32 v3, v3, v2
	v_mul_hi_u32 v3, v2, v3
	v_add_u32_e32 v2, v2, v3
	v_mul_hi_u32 v2, v1, v2
	v_mul_lo_u32 v3, v2, v0
	v_sub_u32_e32 v1, v1, v3
	v_add_u32_e32 v5, 1, v2
	v_cmp_ge_u32_e32 vcc, v1, v0
	v_sub_u32_e32 v3, v1, v0
	s_nop 0
	v_cndmask_b32_e32 v2, v2, v5, vcc
	v_cndmask_b32_e32 v1, v1, v3, vcc
	v_add_u32_e32 v3, 1, v2
	v_cmp_ge_u32_e32 vcc, v1, v0
	s_nop 1
	v_cndmask_b32_e32 v2, v2, v3, vcc
	v_mul_lo_u32 v1, v0, v2
	v_add_u32_e32 v0, v1, v0
	v_cmp_ne_u32_e32 vcc, v4, v0
	v_mov_b32_e32 v232, v0
	v_mov_b64_e32 v[0:1], s[10:11]
	s_and_saveexec_b64 s[8:9], vcc
	s_cbranch_execz .LBB0_1222
	v_mov_b32_e32 v0, 0
	v_mov_b32_e32 v233, 0xe7c4000
	global_load_dword v1, v233, s[86:87] offset:1024 sc1
	s_mov_b64 s[16:17], 0
	s_waitcnt vmcnt(0)
	v_cmp_lt_u32_e32 vcc, v1, v232
	s_and_saveexec_b64 s[14:15], vcc
	s_cbranch_execz .LBB0_1221
	s_add_u32 s12, s86, 0xe7c1200
	s_addc_u32 s13, s87, 0
	s_mov_b32 s0, 1
	s_branch .LBB0_1214

; DI unsigned xb_ld(unsigned* p) { return __hip_atomic_load(p, __ATOMIC_RELAXED, __HIP_MEMORY_SCOPE_AGENT); }
; #define XB_SPIN(cond, bar) do { unsigned _sp = 0; while (cond) { __builtin_amdgcn_s_sleep(1); \
;     if ((++_sp & 255u) == 0u) { if (xb_ld(&(bar)[XB_TMO])) break; if (_sp > XB_SPIN_CAP) { atomicAdd(&(bar)[XB_TMO], 1u); break; } } } } while (0)
; DI void xcd_barrier(const XcdBarrier& b) {
;     ...
;       else XB_SPIN(xb_ld(&bar[XB_TOPGEN]) == tg, bar);
.LBB0_1218:
	global_load_dword v1, v233, s[86:87] offset:1024 sc1
	s_add_i32 s0, s0, 1
	s_mov_b64 s[22:23], -1
	s_waitcnt vmcnt(0)
	v_cmp_ge_u32_e32 vcc, v1, v232
	s_orn2_b64 s[26:27], vcc, exec
	s_branch .LBB0_1213

; DI unsigned xb_ld(unsigned* p) { return __hip_atomic_load(p, __ATOMIC_RELAXED, __HIP_MEMORY_SCOPE_AGENT); }
; #define XB_SPIN(cond, bar) do { unsigned _sp = 0; while (cond) { __builtin_amdgcn_s_sleep(1); \
;     if ((++_sp & 255u) == 0u) { if (xb_ld(&(bar)[XB_TMO])) break; if (_sp > XB_SPIN_CAP) { atomicAdd(&(bar)[XB_TMO], 1u); break; } } } } while (0)
; DI void xcd_barrier(const XcdBarrier& b) {
;     ...
;       else XB_SPIN(xb_ld(&bar[XB_TOPGEN]) == tg, bar);
.LBB0_1342:
	global_load_dword v1, v233, s[86:87] offset:1024 sc1
	s_add_i32 s0, s0, 1
	s_mov_b64 s[20:21], -1
	s_waitcnt vmcnt(0)
	v_cmp_ge_u32_e32 vcc, v1, v232
	s_orn2_b64 s[24:25], vcc, exec
	s_branch .LBB0_1337

; DI unsigned xb_ld(unsigned* p) { return __hip_atomic_load(p, __ATOMIC_RELAXED, __HIP_MEMORY_SCOPE_AGENT); }
; DI unsigned xb_add(unsigned* p, unsigned v) { return __hip_atomic_fetch_add(p, v, __ATOMIC_RELAXED, __HIP_MEMORY_SCOPE_AGENT); }
; #define XB_SPIN(cond, bar) do { unsigned _sp = 0; while (cond) { __builtin_amdgcn_s_sleep(1); \
;     if ((++_sp & 255u) == 0u) { if (xb_ld(&(bar)[XB_TMO])) break; if (_sp > XB_SPIN_CAP) { atomicAdd(&(bar)[XB_TMO], 1u); break; } } } } while (0)
; DI void xcd_barrier(const XcdBarrier& b) {
;     ...
;       const unsigned og = xb_add(&bar[XB_TOP], 1u);
;       const unsigned tg = og / nx;
;       if (og + 1u == (tg + 1u) * nx) xb_add(&bar[XB_TOPGEN], 1u);
;       else XB_SPIN(xb_ld(&bar[XB_TOPGEN]) == tg, bar);
.LBB0_1393:
	s_or_b64 exec, exec, s[12:13]
	v_cvt_f32_u32_e32 v3, v0
	s_waitcnt vmcnt(0)
	v_readfirstlane_b32 s2, v2
	s_add_u32 s12, s86, 0xe7c4500
	s_addc_u32 s13, s87, 0
	v_rcp_iflag_f32_e32 v3, v3
	v_add_u32_e32 v1, s2, v1
	v_add_u32_e32 v4, 1, v1
	s_mov_b64 s[14:15], -1
	v_mul_f32_e32 v2, 0x4f7ffffe, v3
	v_cvt_u32_f32_e32 v2, v2
	v_sub_u32_e32 v3, 0, v0
	v_mul_lo_u32 v3, v3, v2
	v_mul_hi_u32 v3, v2, v3
	v_add_u32_e32 v2, v2, v3
	v_mul_hi_u32 v2, v1, v2
	v_mul_lo_u32 v3, v2, v0
	v_sub_u32_e32 v1, v1, v3
	v_add_u32_e32 v5, 1, v2
	v_cmp_ge_u32_e32 vcc, v1, v0
	v_sub_u32_e32 v3, v1, v0
	s_nop 0
	v_cndmask_b32_e32 v2, v2, v5, vcc
	v_cndmask_b32_e32 v1, v1, v3, vcc
	v_add_u32_e32 v3, 1, v2
	v_cmp_ge_u32_e32 vcc, v1, v0
	s_nop 1
	v_cndmask_b32_e32 v2, v2, v3, vcc
	v_mul_lo_u32 v1, v0, v2
	v_add_u32_e32 v0, v1, v0
	v_cmp_ne_u32_e32 vcc, v4, v0
	v_mov_b32_e32 v232, v0
	v_mov_b64_e32 v[0:1], s[12:13]
	s_and_saveexec_b64 s[8:9], vcc
	s_cbranch_execz .LBB0_1405
	v_mov_b32_e32 v0, 0
	v_mov_b32_e32 v233, 0xe7c4000
	global_load_dword v1, v233, s[86:87] offset:1024 sc1
	s_mov_b64 s[18:19], 0
	s_waitcnt vmcnt(0)
	v_cmp_lt_u32_e32 vcc, v1, v232
	s_and_saveexec_b64 s[16:17], vcc
	s_cbranch_execz .LBB0_1404
	s_add_u32 s14, s86, 0xe7c1200
	s_addc_u32 s15, s87, 0
	s_mov_b32 s3, 1
	s_branch .LBB0_1397

; DI unsigned xb_ld(unsigned* p) { return __hip_atomic_load(p, __ATOMIC_RELAXED, __HIP_MEMORY_SCOPE_AGENT); }
; #define XB_SPIN(cond, bar) do { unsigned _sp = 0; while (cond) { __builtin_amdgcn_s_sleep(1); \
;     if ((++_sp & 255u) == 0u) { if (xb_ld(&(bar)[XB_TMO])) break; if (_sp > XB_SPIN_CAP) { atomicAdd(&(bar)[XB_TMO], 1u); break; } } } } while (0)
; DI void xcd_barrier(const XcdBarrier& b) {
;     ...
;       else XB_SPIN(xb_ld(&bar[XB_TOPGEN]) == tg, bar);
.LBB0_1401:
	global_load_dword v1, v233, s[86:87] offset:1024 sc1
	s_add_i32 s3, s3, 1
	s_mov_b64 s[22:23], -1
	s_waitcnt vmcnt(0)
	v_cmp_ge_u32_e32 vcc, v1, v232
	s_orn2_b64 s[26:27], vcc, exec
	s_branch .LBB0_1396

; DI unsigned xb_ld(unsigned* p) { return __hip_atomic_load(p, __ATOMIC_RELAXED, __HIP_MEMORY_SCOPE_AGENT); }
; DI unsigned xb_add(unsigned* p, unsigned v) { return __hip_atomic_fetch_add(p, v, __ATOMIC_RELAXED, __HIP_MEMORY_SCOPE_AGENT); }
; #define XB_SPIN(cond, bar) do { unsigned _sp = 0; while (cond) { __builtin_amdgcn_s_sleep(1); \
;     if ((++_sp & 255u) == 0u) { if (xb_ld(&(bar)[XB_TMO])) break; if (_sp > XB_SPIN_CAP) { atomicAdd(&(bar)[XB_TMO], 1u); break; } } } } while (0)
; DI void xcd_barrier(const XcdBarrier& b) {
;     ...
;       const unsigned og = xb_add(&bar[XB_TOP], 1u);
;       const unsigned tg = og / nx;
;       if (og + 1u == (tg + 1u) * nx) xb_add(&bar[XB_TOPGEN], 1u);
;       else XB_SPIN(xb_ld(&bar[XB_TOPGEN]) == tg, bar);
.LBB0_1518:
	s_or_b64 exec, exec, s[6:7]
	v_cvt_f32_u32_e32 v3, v0
	s_waitcnt vmcnt(0)
	v_readfirstlane_b32 s4, v2
	s_add_u32 s6, s86, 0xe7c4500
	s_addc_u32 s7, s87, 0
	v_rcp_iflag_f32_e32 v3, v3
	v_add_u32_e32 v1, s4, v1
	v_add_u32_e32 v4, 1, v1
	s_mov_b64 s[8:9], -1
	v_mul_f32_e32 v2, 0x4f7ffffe, v3
	v_cvt_u32_f32_e32 v2, v2
	v_sub_u32_e32 v3, 0, v0
	v_mul_lo_u32 v3, v3, v2
	v_mul_hi_u32 v3, v2, v3
	v_add_u32_e32 v2, v2, v3
	v_mul_hi_u32 v2, v1, v2
	v_mul_lo_u32 v3, v2, v0
	v_sub_u32_e32 v1, v1, v3
	v_add_u32_e32 v5, 1, v2
	v_cmp_ge_u32_e32 vcc, v1, v0
	v_sub_u32_e32 v3, v1, v0
	s_nop 0
	v_cndmask_b32_e32 v2, v2, v5, vcc
	v_cndmask_b32_e32 v1, v1, v3, vcc
	v_add_u32_e32 v3, 1, v2
	v_cmp_ge_u32_e32 vcc, v1, v0
	s_nop 1
	v_cndmask_b32_e32 v2, v2, v3, vcc
	v_mul_lo_u32 v1, v0, v2
	v_add_u32_e32 v0, v1, v0
	v_cmp_ne_u32_e32 vcc, v4, v0
	v_mov_b32_e32 v232, v0
	v_mov_b64_e32 v[0:1], s[6:7]
	s_and_saveexec_b64 s[4:5], vcc
	s_cbranch_execz .LBB0_1530
	v_mov_b32_e32 v0, 0
	v_mov_b32_e32 v233, 0xe7c4000
	global_load_dword v1, v233, s[86:87] offset:1024 sc1
	s_mov_b64 s[12:13], 0
	s_waitcnt vmcnt(0)
	v_cmp_lt_u32_e32 vcc, v1, v232
	s_and_saveexec_b64 s[10:11], vcc
	s_cbranch_execz .LBB0_1529
	s_add_u32 s8, s86, 0xe7c1200
	s_addc_u32 s9, s87, 0
	s_mov_b32 s22, 1
	s_branch .LBB0_1522

; DI unsigned xb_ld(unsigned* p) { return __hip_atomic_load(p, __ATOMIC_RELAXED, __HIP_MEMORY_SCOPE_AGENT); }
; #define XB_SPIN(cond, bar) do { unsigned _sp = 0; while (cond) { __builtin_amdgcn_s_sleep(1); \
;     if ((++_sp & 255u) == 0u) { if (xb_ld(&(bar)[XB_TMO])) break; if (_sp > XB_SPIN_CAP) { atomicAdd(&(bar)[XB_TMO], 1u); break; } } } } while (0)
; DI void xcd_barrier(const XcdBarrier& b) {
;     ...
;       else XB_SPIN(xb_ld(&bar[XB_TOPGEN]) == tg, bar);
.LBB0_1526:
	global_load_dword v1, v233, s[86:87] offset:1024 sc1
	s_add_i32 s22, s22, 1
	s_mov_b64 s[16:17], -1
	s_waitcnt vmcnt(0)
	v_cmp_ge_u32_e32 vcc, v1, v232
	s_orn2_b64 s[20:21], vcc, exec
	s_branch .LBB0_1521
